# NORMMOD row loop hand-written: scalar row addressing, all 24 loads of a 2-row step in flight, g preloaded (was 9 serialized round trips per step)
# speedup vs baseline: 1.1286x; 1.0020x over previous
;   __host__ __device__ __forceinline__ float* ctxres() const { return (float*)(wsl() + OFF_CTXRES); }
;   __host__ __device__ __forceinline__ float* mod() const { return (float*)(wsl() + OFF_MOD); }
; __device__ __forceinline__ int obid() { int t = blockIdx.x; asm volatile("" : "+s"(t)); return t; }
; __device__ __forceinline__ void normmod_phase(const Params& p, int layer, int which, int first) {
;     ...
;   for (int row0 = obid() * 8 + w; row0 < NTOK; row0 += 2 * stride) {
;     float4 v[2][4];
;     bool ok[2];
; #pragma unroll
;     for (int q = 0; q < 2; ++q) {
;       int row = row0 + q * stride;
;       ok[q] = row < NTOK;
;       if (ok[q]) {
;         int b = row >= TPB ? 1 : 0, u = row - b * TPB;
;         const float* x = (u < CTX) ? p.ctxres() + (size_t)(b * CTX + u) * D : xlat + ((size_t)b * SEQ + (u - CTX)) * D;
; #pragma unroll
;         for (int i = 0; i < 4; ++i) v[q][i] = *(const float4*)(x + i * 256 + lane * 4);
;       }
;     }
; #pragma unroll
;     for (int q = 0; q < 2; ++q) {
;       if (!ok[q]) continue;
;       int row = row0 + q * stride;
;       const float* md = p.mod() + ((size_t)layer * 3 + condof(row)) * NMOD + which * 3 * D;
;       float ss = 0;
; #pragma unroll
;       for (int i = 0; i < 4; ++i) ss += v[q][i].x * v[q][i].x + v[q][i].y * v[q][i].y + v[q][i].z * v[q][i].z + v[q][i].w * v[q][i].w;
;       ss = wave_sum(ss);
;       float rstd = rsqrtf(ss * (1.0f / D) + 1e-6f);
.LBB0_919:
	v_readfirstlane_b32 s60, v24
	v_lshlrev_b32_e32 v99, 2, v26
	s_lshl_b32 s62, s80, 3
	s_lshl_b32 s63, s80, 4
	global_load_dwordx4 v[178:181], v[28:29], off offset:0
	global_load_dwordx4 v[182:185], v[28:29], off offset:1024
	global_load_dwordx4 v[186:189], v[28:29], off offset:2048
	global_load_dwordx4 v[190:193], v[28:29], off offset:3072
.Lnm_loop:
	s_add_i32 s61, s60, s62
	s_cmpk_gt_u32 s60, 0x20ff
	s_cselect_b32 s56, 1, 0
	s_mul_i32 s57, s56, 0x2100
	s_sub_i32 s57, s60, s57
	s_cmpk_lt_u32 s57, 0x100
	s_cbranch_scc0 .Lnm_latA
	s_lshl_b32 s58, s56, 8
	s_add_i32 s58, s58, s57
	s_mov_b32 s59, 0
	s_lshl_b64 s[58:59], s[58:59], 12
	s_add_u32 s40, s8, s58
	s_addc_u32 s41, s9, s59
	s_mov_b32 s56, 2
	s_branch .Lnm_mdA
.Lnm_latA:
	s_lshl_b32 s58, s56, 13
	s_add_i32 s58, s58, s57
	s_addk_i32 s58, 0xff00
	s_mov_b32 s59, 0
	s_lshl_b64 s[58:59], s[58:59], 12
	s_add_u32 s40, s6, s58
	s_addc_u32 s41, s7, s59
.Lnm_mdA:
	s_add_i32 s56, s56, s18
	s_mul_i32 s56, s56, 0x9000
	s_add_u32 s42, s10, s56
	s_addc_u32 s43, s11, 0
	s_add_u32 s44, s42, 0x1000
	s_addc_u32 s45, s43, 0
	s_mov_b32 s52, s60
	s_mov_b32 s53, 0
	s_lshl_b64 s[52:53], s[52:53], 11
	global_load_dwordx4 v[0:3], v99, s[40:41] offset:0
	global_load_dwordx4 v[4:7], v99, s[40:41] offset:1024
	global_load_dwordx4 v[8:11], v99, s[40:41] offset:2048
	global_load_dwordx4 v[12:15], v99, s[40:41] offset:3072
	global_load_dwordx4 v[100:103], v99, s[42:43] offset:0
	global_load_dwordx4 v[104:107], v99, s[42:43] offset:1024
	global_load_dwordx4 v[108:111], v99, s[42:43] offset:2048
	global_load_dwordx4 v[112:115], v99, s[42:43] offset:3072
	global_load_dwordx4 v[116:119], v99, s[44:45] offset:0
	global_load_dwordx4 v[120:123], v99, s[44:45] offset:1024
	global_load_dwordx4 v[124:127], v99, s[44:45] offset:2048
	global_load_dwordx4 v[128:131], v99, s[44:45] offset:3072
	s_cmpk_lt_u32 s61, 0x4200
	s_cbranch_scc0 .Lnm_onlyA
	s_cmpk_gt_u32 s61, 0x20ff
	s_cselect_b32 s56, 1, 0
	s_mul_i32 s57, s56, 0x2100
	s_sub_i32 s57, s61, s57
	s_cmpk_lt_u32 s57, 0x100
	s_cbranch_scc0 .Lnm_latB
	s_lshl_b32 s58, s56, 8
	s_add_i32 s58, s58, s57
	s_mov_b32 s59, 0
	s_lshl_b64 s[58:59], s[58:59], 12
	s_add_u32 s46, s8, s58
	s_addc_u32 s47, s9, s59
	s_mov_b32 s56, 2
	s_branch .Lnm_mdB
.Lnm_latB:
	s_lshl_b32 s58, s56, 13
	s_add_i32 s58, s58, s57
	s_addk_i32 s58, 0xff00
	s_mov_b32 s59, 0
	s_lshl_b64 s[58:59], s[58:59], 12
	s_add_u32 s46, s6, s58
	s_addc_u32 s47, s7, s59
.Lnm_mdB:
	s_add_i32 s56, s56, s18
	s_mul_i32 s56, s56, 0x9000
	s_add_u32 s48, s10, s56
	s_addc_u32 s49, s11, 0
	s_add_u32 s50, s48, 0x1000
	s_addc_u32 s51, s49, 0
	s_mov_b32 s54, s61
	s_mov_b32 s55, 0
	s_lshl_b64 s[54:55], s[54:55], 11
	global_load_dwordx4 v[200:203], v99, s[46:47] offset:0
	global_load_dwordx4 v[204:207], v99, s[46:47] offset:1024
	global_load_dwordx4 v[208:211], v99, s[46:47] offset:2048
	global_load_dwordx4 v[212:215], v99, s[46:47] offset:3072
	global_load_dwordx4 v[132:135], v99, s[48:49] offset:0
	global_load_dwordx4 v[136:139], v99, s[48:49] offset:1024
	global_load_dwordx4 v[140:143], v99, s[48:49] offset:2048
	global_load_dwordx4 v[144:147], v99, s[48:49] offset:3072
	global_load_dwordx4 v[148:151], v99, s[50:51] offset:0
	global_load_dwordx4 v[152:155], v99, s[50:51] offset:1024
	global_load_dwordx4 v[156:159], v99, s[50:51] offset:2048
	global_load_dwordx4 v[160:163], v99, s[50:51] offset:3072
	s_waitcnt vmcnt(12)
	v_mul_f32_e32 v40, v0, v0
	v_fmac_f32_e32 v40, v1, v1
	v_fmac_f32_e32 v40, v2, v2
	v_fmac_f32_e32 v40, v3, v3
	v_fmac_f32_e32 v40, v4, v4
	v_fmac_f32_e32 v40, v5, v5
	v_fmac_f32_e32 v40, v6, v6
	v_fmac_f32_e32 v40, v7, v7
	v_fmac_f32_e32 v40, v8, v8
	v_fmac_f32_e32 v40, v9, v9
	v_fmac_f32_e32 v40, v10, v10
	v_fmac_f32_e32 v40, v11, v11
	v_fmac_f32_e32 v40, v12, v12
	v_fmac_f32_e32 v40, v13, v13
	v_fmac_f32_e32 v40, v14, v14
	v_fmac_f32_e32 v40, v15, v15
	ds_bpermute_b32 v41, v27, v40
	s_waitcnt lgkmcnt(0)
	v_add_f32_e32 v40, v40, v41
	ds_bpermute_b32 v41, v31, v40
	s_waitcnt lgkmcnt(0)
	v_add_f32_e32 v40, v40, v41
	ds_bpermute_b32 v41, v33, v40
	s_waitcnt lgkmcnt(0)
	v_add_f32_e32 v40, v40, v41
	ds_bpermute_b32 v41, v35, v40
	s_waitcnt lgkmcnt(0)
	v_add_f32_e32 v40, v40, v41
	ds_bpermute_b32 v41, v68, v40
	s_waitcnt lgkmcnt(0)
	v_add_f32_e32 v40, v40, v41
	ds_bpermute_b32 v41, v69, v40
	s_waitcnt lgkmcnt(0)
;   __host__ __device__ __forceinline__ bf16_t* H() const { return (bf16_t*)(wsl() + OFF_H); }
; __device__ __forceinline__ uint32_t pack2(float a, float b) { uint32_t r; asm("v_cvt_pk_bf16_f32 %0, %1, %2" : "=v"(r) : "v"(a), "v"(b)); return r; }
; __device__ __forceinline__ void normmod_phase(const Params& p, int layer, int which, int first) {
;     ...
;       float rstd = rsqrtf(ss * (1.0f / D) + 1e-6f);
; #pragma unroll
;       for (int i = 0; i < 4; ++i) {
;         int cidx = i * 256 + lane * 4;
;         float4 g4 = *(const float4*)(g + cidx);
;         float4 sh = *(const float4*)(md + cidx);
;         float4 sc = *(const float4*)(md + D + cidx);
;         float h0 = v[q][i].x * rstd * g4.x * (1.0f + sc.x) + sh.x;
;         float h1 = v[q][i].y * rstd * g4.y * (1.0f + sc.y) + sh.y;
;         float h2 = v[q][i].z * rstd * g4.z * (1.0f + sc.z) + sh.z;
;         float h3 = v[q][i].w * rstd * g4.w * (1.0f + sc.w) + sh.w;
;         uint2 o; o.x = pack2(h0, h1); o.y = pack2(h2, h3);
;         *(uint2*)(p.H() + (size_t)row * D + cidx) = o;
;       }
	v_add_f32_e32 v40, v40, v41
	v_fmamk_f32 v40, v40, 0x3a800000, v168
	s_mov_b32 s56, 0x800000
	v_mul_f32_e32 v41, 0x4b800000, v40
	v_cmp_gt_f32_e64 s[58:59], s56, v40
	s_nop 1
	v_cndmask_b32_e64 v40, v40, v41, s[58:59]
	v_rsq_f32_e32 v40, v40
	s_nop 0
	v_mul_f32_e32 v41, 0x45800000, v40
	v_cndmask_b32_e64 v40, v40, v41, s[58:59]
	v_lshl_add_u64 v[62:63], v[36:37], 0, s[52:53]
	v_mul_f32_e32 v0, v0, v40
	v_mul_f32_e32 v0, v178, v0
	v_add_f32_e32 v42, 1.0, v116
	v_mul_f32_e32 v1, v1, v40
	v_mul_f32_e32 v1, v179, v1
	v_add_f32_e32 v43, 1.0, v117
	v_mul_f32_e32 v2, v2, v40
	v_mul_f32_e32 v2, v180, v2
	v_add_f32_e32 v44, 1.0, v118
	v_mul_f32_e32 v3, v3, v40
	v_mul_f32_e32 v3, v181, v3
	v_add_f32_e32 v45, 1.0, v119
	v_fma_f32 v0, v42, v0, v100
	v_fma_f32 v1, v43, v1, v101
	v_fma_f32 v2, v44, v2, v102
	v_fma_f32 v3, v45, v3, v103
	v_cvt_pk_bf16_f32 v0, v0, v1
	v_cvt_pk_bf16_f32 v1, v2, v3
	global_store_dwordx2 v[62:63], v[0:1], off offset:0
	v_mul_f32_e32 v4, v4, v40
	v_mul_f32_e32 v4, v182, v4
	v_add_f32_e32 v42, 1.0, v120
	v_mul_f32_e32 v5, v5, v40
	v_mul_f32_e32 v5, v183, v5
	v_add_f32_e32 v43, 1.0, v121
	v_mul_f32_e32 v6, v6, v40
	v_mul_f32_e32 v6, v184, v6
	v_add_f32_e32 v44, 1.0, v122
	v_mul_f32_e32 v7, v7, v40
	v_mul_f32_e32 v7, v185, v7
	v_add_f32_e32 v45, 1.0, v123
	v_fma_f32 v4, v42, v4, v104
	v_fma_f32 v5, v43, v5, v105
	v_fma_f32 v6, v44, v6, v106
	v_fma_f32 v7, v45, v7, v107
	v_cvt_pk_bf16_f32 v4, v4, v5
	v_cvt_pk_bf16_f32 v5, v6, v7
	global_store_dwordx2 v[62:63], v[4:5], off offset:512
	v_mul_f32_e32 v8, v8, v40
	v_mul_f32_e32 v8, v186, v8
	v_add_f32_e32 v42, 1.0, v124
	v_mul_f32_e32 v9, v9, v40
	v_mul_f32_e32 v9, v187, v9
	v_add_f32_e32 v43, 1.0, v125
	v_mul_f32_e32 v10, v10, v40
	v_mul_f32_e32 v10, v188, v10
	v_add_f32_e32 v44, 1.0, v126
	v_mul_f32_e32 v11, v11, v40
	v_mul_f32_e32 v11, v189, v11
	v_add_f32_e32 v45, 1.0, v127
	v_fma_f32 v8, v42, v8, v108
	v_fma_f32 v9, v43, v9, v109
	v_fma_f32 v10, v44, v10, v110
	v_fma_f32 v11, v45, v11, v111
	v_cvt_pk_bf16_f32 v8, v8, v9
	v_cvt_pk_bf16_f32 v9, v10, v11
	global_store_dwordx2 v[62:63], v[8:9], off offset:1024
	v_mul_f32_e32 v12, v12, v40
	v_mul_f32_e32 v12, v190, v12
	v_add_f32_e32 v42, 1.0, v128
	v_mul_f32_e32 v13, v13, v40
	v_mul_f32_e32 v13, v191, v13
	v_add_f32_e32 v43, 1.0, v129
	v_mul_f32_e32 v14, v14, v40
	v_mul_f32_e32 v14, v192, v14
	v_add_f32_e32 v44, 1.0, v130
	v_mul_f32_e32 v15, v15, v40
	v_mul_f32_e32 v15, v193, v15
	v_add_f32_e32 v45, 1.0, v131
	v_fma_f32 v12, v42, v12, v112
	v_fma_f32 v13, v43, v13, v113
	v_fma_f32 v14, v44, v14, v114
	v_fma_f32 v15, v45, v15, v115
	v_cvt_pk_bf16_f32 v12, v12, v13
	v_cvt_pk_bf16_f32 v13, v14, v15
	global_store_dwordx2 v[62:63], v[12:13], off offset:1536
	s_waitcnt vmcnt(4)
	v_mul_f32_e32 v40, v200, v200
	v_fmac_f32_e32 v40, v201, v201
	v_fmac_f32_e32 v40, v202, v202
	v_fmac_f32_e32 v40, v203, v203
	v_fmac_f32_e32 v40, v204, v204
	v_fmac_f32_e32 v40, v205, v205
	v_fmac_f32_e32 v40, v206, v206
	v_fmac_f32_e32 v40, v207, v207
	v_fmac_f32_e32 v40, v208, v208
	v_fmac_f32_e32 v40, v209, v209
	v_fmac_f32_e32 v40, v210, v210
	v_fmac_f32_e32 v40, v211, v211
	v_fmac_f32_e32 v40, v212, v212
	v_fmac_f32_e32 v40, v213, v213
	v_fmac_f32_e32 v40, v214, v214
	v_fmac_f32_e32 v40, v215, v215
	ds_bpermute_b32 v41, v27, v40
	s_waitcnt lgkmcnt(0)
	v_add_f32_e32 v40, v40, v41
	ds_bpermute_b32 v41, v31, v40
	s_waitcnt lgkmcnt(0)
	v_add_f32_e32 v40, v40, v41
	ds_bpermute_b32 v41, v33, v40
	s_waitcnt lgkmcnt(0)
	v_add_f32_e32 v40, v40, v41
	ds_bpermute_b32 v41, v35, v40
	s_waitcnt lgkmcnt(0)
	v_add_f32_e32 v40, v40, v41
	ds_bpermute_b32 v41, v68, v40
	s_waitcnt lgkmcnt(0)
	v_add_f32_e32 v40, v40, v41
	ds_bpermute_b32 v41, v69, v40
	s_waitcnt lgkmcnt(0)
	v_add_f32_e32 v40, v40, v41
	v_fmamk_f32 v40, v40, 0x3a800000, v168
	s_mov_b32 s56, 0x800000
	v_mul_f32_e32 v41, 0x4b800000, v40
	v_cmp_gt_f32_e64 s[58:59], s56, v40
	s_nop 1
	v_cndmask_b32_e64 v40, v40, v41, s[58:59]
	v_rsq_f32_e32 v40, v40
	s_nop 0
	v_mul_f32_e32 v41, 0x45800000, v40
	v_cndmask_b32_e64 v40, v40, v41, s[58:59]
	v_lshl_add_u64 v[62:63], v[36:37], 0, s[54:55]
	v_mul_f32_e32 v200, v200, v40
	v_mul_f32_e32 v200, v178, v200
	v_add_f32_e32 v42, 1.0, v148
	v_mul_f32_e32 v201, v201, v40
	v_mul_f32_e32 v201, v179, v201
	v_add_f32_e32 v43, 1.0, v149
	v_mul_f32_e32 v202, v202, v40
	v_mul_f32_e32 v202, v180, v202
	v_add_f32_e32 v44, 1.0, v150
	v_mul_f32_e32 v203, v203, v40
	v_mul_f32_e32 v203, v181, v203
	v_add_f32_e32 v45, 1.0, v151
	v_fma_f32 v200, v42, v200, v132
	v_fma_f32 v201, v43, v201, v133
	v_fma_f32 v202, v44, v202, v134
	v_fma_f32 v203, v45, v203, v135
	v_cvt_pk_bf16_f32 v200, v200, v201
	v_cvt_pk_bf16_f32 v201, v202, v203
	global_store_dwordx2 v[62:63], v[200:201], off offset:0
	v_mul_f32_e32 v204, v204, v40
	v_mul_f32_e32 v204, v182, v204
	v_add_f32_e32 v42, 1.0, v152
	v_mul_f32_e32 v205, v205, v40
	v_mul_f32_e32 v205, v183, v205
	v_add_f32_e32 v43, 1.0, v153
	v_mul_f32_e32 v206, v206, v40
	v_mul_f32_e32 v206, v184, v206
	v_add_f32_e32 v44, 1.0, v154
	v_mul_f32_e32 v207, v207, v40
	v_mul_f32_e32 v207, v185, v207
	v_add_f32_e32 v45, 1.0, v155
	v_fma_f32 v204, v42, v204, v136
	v_fma_f32 v205, v43, v205, v137
	v_fma_f32 v206, v44, v206, v138
	v_fma_f32 v207, v45, v207, v139
	v_cvt_pk_bf16_f32 v204, v204, v205
	v_cvt_pk_bf16_f32 v205, v206, v207
	global_store_dwordx2 v[62:63], v[204:205], off offset:512
	v_mul_f32_e32 v208, v208, v40
	v_mul_f32_e32 v208, v186, v208
	v_add_f32_e32 v42, 1.0, v156
	v_mul_f32_e32 v209, v209, v40
	v_mul_f32_e32 v209, v187, v209
	v_add_f32_e32 v43, 1.0, v157
	v_mul_f32_e32 v210, v210, v40
	v_mul_f32_e32 v210, v188, v210
	v_add_f32_e32 v44, 1.0, v158
	v_mul_f32_e32 v211, v211, v40
	v_mul_f32_e32 v211, v189, v211
	v_add_f32_e32 v45, 1.0, v159
	v_fma_f32 v208, v42, v208, v140
	v_fma_f32 v209, v43, v209, v141
	v_fma_f32 v210, v44, v210, v142
	v_fma_f32 v211, v45, v211, v143
	v_cvt_pk_bf16_f32 v208, v208, v209
	v_cvt_pk_bf16_f32 v209, v210, v211
	global_store_dwordx2 v[62:63], v[208:209], off offset:1024
	v_mul_f32_e32 v212, v212, v40
	v_mul_f32_e32 v212, v190, v212
	v_add_f32_e32 v42, 1.0, v160
	v_mul_f32_e32 v213, v213, v40
	v_mul_f32_e32 v213, v191, v213
	v_add_f32_e32 v43, 1.0, v161
	v_mul_f32_e32 v214, v214, v40
	v_mul_f32_e32 v214, v192, v214
	v_add_f32_e32 v44, 1.0, v162
	v_mul_f32_e32 v215, v215, v40
	v_mul_f32_e32 v215, v193, v215
	v_add_f32_e32 v45, 1.0, v163
	v_fma_f32 v212, v42, v212, v144
	v_fma_f32 v213, v43, v213, v145
	v_fma_f32 v214, v44, v214, v146
	v_fma_f32 v215, v45, v215, v147
	v_cvt_pk_bf16_f32 v212, v212, v213
	v_cvt_pk_bf16_f32 v213, v214, v215
	global_store_dwordx2 v[62:63], v[212:213], off offset:1536
	s_branch .Lnm_next
;   __host__ __device__ __forceinline__ float* mod() const { return (float*)(wsl() + OFF_MOD); }
;   __host__ __device__ __forceinline__ bf16_t* H() const { return (bf16_t*)(wsl() + OFF_H); }
; __device__ __forceinline__ uint32_t pack2(float a, float b) { uint32_t r; asm("v_cvt_pk_bf16_f32 %0, %1, %2" : "=v"(r) : "v"(a), "v"(b)); return r; }
; __device__ __forceinline__ void normmod_phase(const Params& p, int layer, int which, int first) {
;     ...
; #pragma unroll
;     for (int q = 0; q < 2; ++q) {
;       if (!ok[q]) continue;
;       int row = row0 + q * stride;
;       const float* md = p.mod() + ((size_t)layer * 3 + condof(row)) * NMOD + which * 3 * D;
;       float ss = 0;
; #pragma unroll
;       for (int i = 0; i < 4; ++i) ss += v[q][i].x * v[q][i].x + v[q][i].y * v[q][i].y + v[q][i].z * v[q][i].z + v[q][i].w * v[q][i].w;
;       ss = wave_sum(ss);
;       float rstd = rsqrtf(ss * (1.0f / D) + 1e-6f);
; #pragma unroll
;       for (int i = 0; i < 4; ++i) {
;         int cidx = i * 256 + lane * 4;
;         float4 g4 = *(const float4*)(g + cidx);
;         float4 sh = *(const float4*)(md + cidx);
;         float4 sc = *(const float4*)(md + D + cidx);
;         float h0 = v[q][i].x * rstd * g4.x * (1.0f + sc.x) + sh.x;
;         float h1 = v[q][i].y * rstd * g4.y * (1.0f + sc.y) + sh.y;
;         float h2 = v[q][i].z * rstd * g4.z * (1.0f + sc.z) + sh.z;
;         float h3 = v[q][i].w * rstd * g4.w * (1.0f + sc.w) + sh.w;
;         uint2 o; o.x = pack2(h0, h1); o.y = pack2(h2, h3);
;         *(uint2*)(p.H() + (size_t)row * D + cidx) = o;
;       }
;     }
;   }
.Lnm_onlyA:
	s_waitcnt vmcnt(0)
	v_mul_f32_e32 v40, v0, v0
	v_fmac_f32_e32 v40, v1, v1
	v_fmac_f32_e32 v40, v2, v2
	v_fmac_f32_e32 v40, v3, v3
	v_fmac_f32_e32 v40, v4, v4
	v_fmac_f32_e32 v40, v5, v5
	v_fmac_f32_e32 v40, v6, v6
	v_fmac_f32_e32 v40, v7, v7
	v_fmac_f32_e32 v40, v8, v8
	v_fmac_f32_e32 v40, v9, v9
	v_fmac_f32_e32 v40, v10, v10
	v_fmac_f32_e32 v40, v11, v11
	v_fmac_f32_e32 v40, v12, v12
	v_fmac_f32_e32 v40, v13, v13
	v_fmac_f32_e32 v40, v14, v14
	v_fmac_f32_e32 v40, v15, v15
	ds_bpermute_b32 v41, v27, v40
	s_waitcnt lgkmcnt(0)
	v_add_f32_e32 v40, v40, v41
	ds_bpermute_b32 v41, v31, v40
	s_waitcnt lgkmcnt(0)
	v_add_f32_e32 v40, v40, v41
	ds_bpermute_b32 v41, v33, v40
	s_waitcnt lgkmcnt(0)
	v_add_f32_e32 v40, v40, v41
	ds_bpermute_b32 v41, v35, v40
	s_waitcnt lgkmcnt(0)
	v_add_f32_e32 v40, v40, v41
	ds_bpermute_b32 v41, v68, v40
	s_waitcnt lgkmcnt(0)
	v_add_f32_e32 v40, v40, v41
	ds_bpermute_b32 v41, v69, v40
	s_waitcnt lgkmcnt(0)
	v_add_f32_e32 v40, v40, v41
	v_fmamk_f32 v40, v40, 0x3a800000, v168
	s_mov_b32 s56, 0x800000
	v_mul_f32_e32 v41, 0x4b800000, v40
	v_cmp_gt_f32_e64 s[58:59], s56, v40
	s_nop 1
	v_cndmask_b32_e64 v40, v40, v41, s[58:59]
	v_rsq_f32_e32 v40, v40
	s_nop 0
	v_mul_f32_e32 v41, 0x45800000, v40
	v_cndmask_b32_e64 v40, v40, v41, s[58:59]
	v_lshl_add_u64 v[62:63], v[36:37], 0, s[52:53]
	v_mul_f32_e32 v0, v0, v40
	v_mul_f32_e32 v0, v178, v0
	v_add_f32_e32 v42, 1.0, v116
	v_mul_f32_e32 v1, v1, v40
	v_mul_f32_e32 v1, v179, v1
	v_add_f32_e32 v43, 1.0, v117
	v_mul_f32_e32 v2, v2, v40
	v_mul_f32_e32 v2, v180, v2
	v_add_f32_e32 v44, 1.0, v118
	v_mul_f32_e32 v3, v3, v40
	v_mul_f32_e32 v3, v181, v3
	v_add_f32_e32 v45, 1.0, v119
	v_fma_f32 v0, v42, v0, v100
	v_fma_f32 v1, v43, v1, v101
	v_fma_f32 v2, v44, v2, v102
	v_fma_f32 v3, v45, v3, v103
	v_cvt_pk_bf16_f32 v0, v0, v1
	v_cvt_pk_bf16_f32 v1, v2, v3
	global_store_dwordx2 v[62:63], v[0:1], off offset:0
	v_mul_f32_e32 v4, v4, v40
	v_mul_f32_e32 v4, v182, v4
	v_add_f32_e32 v42, 1.0, v120
	v_mul_f32_e32 v5, v5, v40
	v_mul_f32_e32 v5, v183, v5
	v_add_f32_e32 v43, 1.0, v121
	v_mul_f32_e32 v6, v6, v40
	v_mul_f32_e32 v6, v184, v6
	v_add_f32_e32 v44, 1.0, v122
	v_mul_f32_e32 v7, v7, v40
	v_mul_f32_e32 v7, v185, v7
	v_add_f32_e32 v45, 1.0, v123
	v_fma_f32 v4, v42, v4, v104
	v_fma_f32 v5, v43, v5, v105
	v_fma_f32 v6, v44, v6, v106
	v_fma_f32 v7, v45, v7, v107
	v_cvt_pk_bf16_f32 v4, v4, v5
	v_cvt_pk_bf16_f32 v5, v6, v7
	global_store_dwordx2 v[62:63], v[4:5], off offset:512
	v_mul_f32_e32 v8, v8, v40
	v_mul_f32_e32 v8, v186, v8
	v_add_f32_e32 v42, 1.0, v124
	v_mul_f32_e32 v9, v9, v40
	v_mul_f32_e32 v9, v187, v9
	v_add_f32_e32 v43, 1.0, v125
	v_mul_f32_e32 v10, v10, v40
	v_mul_f32_e32 v10, v188, v10
	v_add_f32_e32 v44, 1.0, v126
	v_mul_f32_e32 v11, v11, v40
	v_mul_f32_e32 v11, v189, v11
	v_add_f32_e32 v45, 1.0, v127
	v_fma_f32 v8, v42, v8, v108
	v_fma_f32 v9, v43, v9, v109
	v_fma_f32 v10, v44, v10, v110
	v_fma_f32 v11, v45, v11, v111
	v_cvt_pk_bf16_f32 v8, v8, v9
	v_cvt_pk_bf16_f32 v9, v10, v11
	global_store_dwordx2 v[62:63], v[8:9], off offset:1024
	v_mul_f32_e32 v12, v12, v40
	v_mul_f32_e32 v12, v190, v12
	v_add_f32_e32 v42, 1.0, v128
	v_mul_f32_e32 v13, v13, v40
	v_mul_f32_e32 v13, v191, v13
	v_add_f32_e32 v43, 1.0, v129
	v_mul_f32_e32 v14, v14, v40
	v_mul_f32_e32 v14, v192, v14
	v_add_f32_e32 v44, 1.0, v130
	v_mul_f32_e32 v15, v15, v40
	v_mul_f32_e32 v15, v193, v15
	v_add_f32_e32 v45, 1.0, v131
	v_fma_f32 v12, v42, v12, v112
	v_fma_f32 v13, v43, v13, v113
	v_fma_f32 v14, v44, v14, v114
	v_fma_f32 v15, v45, v15, v115
	v_cvt_pk_bf16_f32 v12, v12, v13
	v_cvt_pk_bf16_f32 v13, v14, v15
	global_store_dwordx2 v[62:63], v[12:13], off offset:1536
.Lnm_next:
	s_add_i32 s60, s60, s63
	s_cmpk_lt_u32 s60, 0x4200
	s_cbranch_scc1 .Lnm_loop
